# mLSTM output phase (m_out) unit tail: its 16 gate/normaliser loads issued together after the barrier (were six dependent batches); waits re-derived
# speedup vs baseline: 1.1358x; 1.0004x over previous
; DI unsigned pk2(float lo, float hi) { f32x2 v = {lo, hi}; bf16x2_t b = __builtin_convertvector(v, bf16x2_t); return __builtin_bit_cast(unsigned, b); }
; DI float bflo(unsigned u) { return __uint_as_float(u << 16); }
; DI float bfhi(unsigned u) { return __uint_as_float(u & 0xffff0000u); }
; DI float sigmoidf_(float x) { return __builtin_amdgcn_rcpf(1.f + fexp(-x)); }
; DI void phase_m_out(int wv, const ArgP a, LAS unsigned char* lds, int dry) {
;     ...
;         float rn[2];
; #pragma unroll
;         for (int tb = 0; tb < 2; ++tb) { float s = 0.f;
; #pragma unroll
;             for (int ww = 0; ww < 8; ++ww) s += f_part[ww * 64 + 32 * tb + r32];
;             rn[tb] = rsqrtf(s * (1.f / 256.f) + EPS); }
; #pragma unroll
;         for (int tb = 0; tb < 2; ++tb) { bf16_t* op = QOK + (t0 + 32 * tb + r32) * 2048 + 512 + h * 256 + 32 * w;
; #pragma unroll
;             for (int p = 0; p < 2; ++p) {
;                 unsigned pk[2][2];
; #pragma unroll
;                 for (int q = 0; q < 2; ++q) { const int g = 2 * p + q, dv = 8 * g + 4 * hi; const u32x2 ov = *(const u32x2*)(op + dv);
;                     const f32x4 gg = *(const f32x4*)(ong + h * 256 + 32 * w + dv);
;                     const float og[4] = {bflo(ov.x), bfhi(ov.x), bflo(ov.y), bfhi(ov.y)}; float y[4];
; #pragma unroll
;                     for (int j = 0; j < 4; ++j) { const float hv = (tb ? acc1[4 * g + j] : acc0[4 * g + j]) * rn[tb]; y[j] = hv * gg[j] * sigmoidf_(og[j]); }
;                     pk[q][0] = pk2(y[0], y[1]); pk[q][1] = pk2(y[2], y[3]); }
;                 const auto r0 = __builtin_amdgcn_permlane32_swap(pk[0][0], pk[1][0], false, false), r1 = __builtin_amdgcn_permlane32_swap(pk[0][1], pk[1][1], false, false);
;                 if (!dry) *(u32x4*)(op + 16 * p + 8 * hi) = (u32x4){r0[0], r1[0], r0[1], r1[1]}; } }
.LBB0_1605:
	s_or_b64 exec, exec, s[48:49]
	v_mov_b32_e32 v9, s69
	v_or_b32_e32 v8, s68, v34
	v_lshlrev_b64 v[8:9], 12, v[8:9]
	v_lshl_add_u64 v[8:9], s[2:3], 0, v[8:9]
	s_lshl_b32 s0, s67, 1
	v_lshl_add_u64 v[8:9], v[8:9], 0, s[0:1]
	s_lshl_b32 s0, s67, 2
	v_lshl_add_u64 v[30:31], s[60:61], 1, v[8:9]
	v_mov_b32_e32 v57, v37
	v_lshl_add_u64 v[8:9], v[54:55], 0, s[0:1]
	s_waitcnt lgkmcnt(0)
	s_barrier
	v_lshl_add_u64 v[104:105], v[30:31], 0, v[56:57]
	v_lshl_add_u64 v[106:107], v[30:31], 0, s[64:65]
	v_lshl_add_u64 v[106:107], v[106:107], 0, v[56:57]
	global_load_dwordx4 v[140:143], v[8:9], off
	global_load_dwordx2 v[144:145], v[104:105], off offset:1024
	global_load_dwordx2 v[146:147], v[104:105], off offset:1040
	global_load_dwordx4 v[148:151], v[8:9], off offset:32
	global_load_dwordx2 v[152:153], v[104:105], off offset:1056
	global_load_dwordx2 v[154:155], v[104:105], off offset:1072
	global_load_dwordx4 v[156:159], v[8:9], off offset:64
	global_load_dwordx4 v[160:163], v[8:9], off offset:96
	global_load_dwordx2 v[164:165], v[106:107], off
	global_load_dwordx2 v[166:167], v[106:107], off offset:16
	global_load_dwordx4 v[168:171], v[8:9], off
	global_load_dwordx4 v[172:175], v[8:9], off offset:32
	global_load_dwordx2 v[176:177], v[106:107], off offset:32
	global_load_dwordx2 v[178:179], v[106:107], off offset:48
	global_load_dwordx4 v[180:183], v[8:9], off offset:64
	global_load_dwordx4 v[184:187], v[8:9], off offset:96
	v_lshl_add_u64 v[84:85], v[30:31], 0, v[56:57]
	ds_read2_b32 v[14:15], v75 offset0:192 offset1:224
	v_add_u32_e32 v75, 0xb800, v35
	v_add_u32_e32 v80, 0xbc00, v35
	ds_read2_b32 v[28:29], v75 offset1:32
	ds_read2_b32 v[90:91], v75 offset0:64 offset1:96
	ds_read2_b32 v[92:93], v75 offset0:128 offset1:160
	ds_read2_b32 v[94:95], v75 offset0:192 offset1:224
	ds_read2_b32 v[96:97], v80 offset1:32
	ds_read2_b32 v[98:99], v80 offset0:64 offset1:96
	ds_read2_b32 v[100:101], v80 offset0:128 offset1:160
	s_waitcnt lgkmcnt(7)
	v_mov_b32_e32 v102, v15
	v_mov_b32_e32 v103, v14
	v_pk_add_f32 v[14:15], v[102:103], 0 op_sel_hi:[1,0]
	s_waitcnt lgkmcnt(6)
	v_mov_b32_e32 v102, v29
	v_mov_b32_e32 v103, v28
	s_waitcnt lgkmcnt(5)
	v_mov_b32_e32 v28, v91
	v_mov_b32_e32 v29, v90
	v_pk_add_f32 v[14:15], v[14:15], v[102:103]
	s_waitcnt lgkmcnt(4)
	v_mov_b32_e32 v90, v93
	v_mov_b32_e32 v91, v92
	v_pk_add_f32 v[14:15], v[14:15], v[28:29]
	s_waitcnt lgkmcnt(3)
	v_mov_b32_e32 v92, v95
	v_mov_b32_e32 v93, v94
	v_pk_add_f32 v[14:15], v[14:15], v[90:91]
	s_waitcnt lgkmcnt(2)
	v_mov_b32_e32 v94, v97
	v_mov_b32_e32 v95, v96
	v_pk_add_f32 v[14:15], v[14:15], v[92:93]
	s_waitcnt lgkmcnt(1)
	v_mov_b32_e32 v96, v99
	v_mov_b32_e32 v97, v98
	v_pk_add_f32 v[14:15], v[14:15], v[94:95]
	s_waitcnt lgkmcnt(0)
	v_mov_b32_e32 v98, v101
	v_mov_b32_e32 v99, v100
	v_pk_add_f32 v[14:15], v[14:15], v[96:97]
	s_nop 0
	v_pk_add_f32 v[14:15], v[14:15], v[98:99]
	s_add_i32 s66, s66, s73
	v_pk_fma_f32 v[14:15], v[14:15], s[62:63], v[58:59] op_sel_hi:[1,0,0]
	s_cmpk_lt_i32 s66, 0x400
	v_mul_f32_e32 v28, 0x4b800000, v15
	v_cmp_gt_f32_e32 vcc, s75, v15
	s_nop 1
	v_cndmask_b32_e32 v15, v15, v28, vcc
	v_rsq_f32_e32 v15, v15
	v_lshl_add_u64 v[28:29], v[30:31], 0, v[36:37]
	v_lshl_add_u64 v[30:31], v[30:31], 0, s[64:65]
	v_mul_f32_e32 v75, 0x45800000, v15
	v_cndmask_b32_e32 v92, v15, v75, vcc
	v_pk_mul_f32 v[64:65], v[64:65], v[92:93] op_sel_hi:[1,0]
	v_pk_mul_f32 v[66:67], v[66:67], v[92:93] op_sel_hi:[1,0]
	v_pk_mul_f32 v[62:63], v[62:63], v[92:93] op_sel_hi:[1,0]
	v_pk_mul_f32 v[60:61], v[60:61], v[92:93] op_sel_hi:[1,0]
	v_pk_mul_f32 v[24:25], v[24:25], v[92:93] op_sel_hi:[1,0]
	v_pk_mul_f32 v[26:27], v[26:27], v[92:93] op_sel_hi:[1,0]
	v_pk_mul_f32 v[10:11], v[10:11], v[92:93] op_sel_hi:[1,0]
	v_pk_mul_f32 v[12:13], v[12:13], v[92:93] op_sel_hi:[1,0]
	v_cmp_gt_f32_e32 vcc, s75, v14
	s_waitcnt vmcnt(15)
	v_pk_mul_f32 v[64:65], v[64:65], v[140:141]
	s_waitcnt vmcnt(14)
	v_lshlrev_b32_e32 v15, 16, v144
	v_and_b32_e32 v75, 0xffff0000, v144
	v_lshlrev_b32_e32 v76, 16, v145
	v_and_b32_e32 v77, 0xffff0000, v145
	v_mul_f32_e32 v15, 0xbfb8aa3b, v15
	v_mul_f32_e32 v75, 0xbfb8aa3b, v75
	v_mul_f32_e32 v76, 0xbfb8aa3b, v76
	v_mul_f32_e32 v77, 0xbfb8aa3b, v77
	v_exp_f32_e32 v15, v15
	v_exp_f32_e32 v75, v75
	v_exp_f32_e32 v76, v76
	v_exp_f32_e32 v77, v77
	v_pk_mul_f32 v[66:67], v[66:67], v[142:143]
	s_waitcnt vmcnt(13)
	v_lshlrev_b32_e32 v78, 16, v146
	v_and_b32_e32 v79, 0xffff0000, v146
	v_mul_f32_e32 v78, 0xbfb8aa3b, v78
	v_lshlrev_b32_e32 v86, 16, v147
	v_and_b32_e32 v87, 0xffff0000, v147
	v_mul_f32_e32 v88, 0xbfb8aa3b, v79
	v_exp_f32_e32 v89, v78
	v_add_f32_e32 v15, 1.0, v15
	v_add_f32_e32 v75, 1.0, v75
	v_add_f32_e32 v78, 1.0, v76
	v_add_f32_e32 v79, 1.0, v77
	v_rcp_f32_e32 v76, v15
	v_rcp_f32_e32 v77, v75
	v_rcp_f32_e32 v78, v78
	v_rcp_f32_e32 v79, v79
	v_exp_f32_e32 v15, v88
	v_pk_mul_f32 v[64:65], v[64:65], v[76:77]
	v_add_f32_e32 v75, 1.0, v89
	v_pk_mul_f32 v[66:67], v[66:67], v[78:79]
	v_add_f32_e32 v15, 1.0, v15
	v_cvt_pk_bf16_f32 v64, v64, v65
	v_cvt_pk_bf16_f32 v65, v66, v67
	v_rcp_f32_e32 v67, v15
	v_mul_f32_e32 v15, 0xbfb8aa3b, v86
	v_rcp_f32_e32 v66, v75
	v_exp_f32_e32 v15, v15
	v_mul_f32_e32 v75, 0xbfb8aa3b, v87
	v_exp_f32_e32 v75, v75
	s_waitcnt vmcnt(12)
	v_pk_mul_f32 v[62:63], v[62:63], v[148:149]
	v_add_f32_e32 v15, 1.0, v15
	v_rcp_f32_e32 v76, v15
	v_add_f32_e32 v15, 1.0, v75
	v_rcp_f32_e32 v77, v15
	v_pk_mul_f32 v[60:61], v[60:61], v[150:151]
	v_pk_mul_f32 v[62:63], v[62:63], v[66:67]
	s_waitcnt vmcnt(11)
; DI unsigned pk2(float lo, float hi) { f32x2 v = {lo, hi}; bf16x2_t b = __builtin_convertvector(v, bf16x2_t); return __builtin_bit_cast(unsigned, b); }
; DI float bflo(unsigned u) { return __uint_as_float(u << 16); }
; DI float bfhi(unsigned u) { return __uint_as_float(u & 0xffff0000u); }
; DI float sigmoidf_(float x) { return __builtin_amdgcn_rcpf(1.f + fexp(-x)); }
; DI void phase_m_out(int wv, const ArgP a, LAS unsigned char* lds, int dry) {
;     ...
; #pragma unroll
;         for (int tb = 0; tb < 2; ++tb) { bf16_t* op = QOK + (t0 + 32 * tb + r32) * 2048 + 512 + h * 256 + 32 * w;
; #pragma unroll
;             for (int p = 0; p < 2; ++p) {
;                 unsigned pk[2][2];
; #pragma unroll
;                 for (int q = 0; q < 2; ++q) { const int g = 2 * p + q, dv = 8 * g + 4 * hi; const u32x2 ov = *(const u32x2*)(op + dv);
;                     const f32x4 gg = *(const f32x4*)(ong + h * 256 + 32 * w + dv);
;                     const float og[4] = {bflo(ov.x), bfhi(ov.x), bflo(ov.y), bfhi(ov.y)}; float y[4];
; #pragma unroll
;                     for (int j = 0; j < 4; ++j) { const float hv = (tb ? acc1[4 * g + j] : acc0[4 * g + j]) * rn[tb]; y[j] = hv * gg[j] * sigmoidf_(og[j]); }
;                     pk[q][0] = pk2(y[0], y[1]); pk[q][1] = pk2(y[2], y[3]); }
;                 const auto r0 = __builtin_amdgcn_permlane32_swap(pk[0][0], pk[1][0], false, false), r1 = __builtin_amdgcn_permlane32_swap(pk[0][1], pk[1][1], false, false);
;                 if (!dry) *(u32x4*)(op + 16 * p + 8 * hi) = (u32x4){r0[0], r1[0], r0[1], r1[1]}; } }
	v_lshlrev_b32_e32 v15, 16, v152
	v_pk_mul_f32 v[60:61], v[60:61], v[76:77]
	v_cvt_pk_bf16_f32 v66, v62, v63
	v_cvt_pk_bf16_f32 v67, v60, v61
	s_nop 0
	v_permlane32_swap_b32_e32 v64, v66
	v_permlane32_swap_b32_e32 v65, v67
	global_store_dwordx4 v[28:29], v[64:67], off offset:1024
	s_nop 0
	v_lshl_add_u64 v[76:77], v[30:31], 0, v[56:57]
	v_and_b32_e32 v57, 0xffff0000, v152
	v_lshlrev_b32_e32 v75, 16, v153
	v_and_b32_e32 v82, 0xffff0000, v153
	s_waitcnt vmcnt(11)
	v_lshlrev_b32_e32 v83, 16, v154
	v_and_b32_e32 v84, 0xffff0000, v154
	v_lshlrev_b32_e32 v86, 16, v155
	v_and_b32_e32 v85, 0xffff0000, v155
	v_mul_f32_e32 v15, 0xbfb8aa3b, v15
	v_mul_f32_e32 v57, 0xbfb8aa3b, v57
	v_mul_f32_e32 v75, 0xbfb8aa3b, v75
	v_mul_f32_e32 v82, 0xbfb8aa3b, v82
	v_mul_f32_e32 v83, 0xbfb8aa3b, v83
	v_mul_f32_e32 v84, 0xbfb8aa3b, v84
	v_mul_f32_e32 v86, 0xbfb8aa3b, v86
	v_mul_f32_e32 v85, 0xbfb8aa3b, v85
	v_exp_f32_e32 v15, v15
	v_exp_f32_e32 v57, v57
	v_exp_f32_e32 v75, v75
	v_exp_f32_e32 v82, v82
	v_exp_f32_e32 v83, v83
	v_exp_f32_e32 v84, v84
	v_exp_f32_e32 v86, v86
	v_exp_f32_e32 v85, v85
	v_add_f32_e32 v15, 1.0, v15
	v_add_f32_e32 v57, 1.0, v57
	v_add_f32_e32 v75, 1.0, v75
	v_add_f32_e32 v87, 1.0, v82
	v_add_f32_e32 v88, 1.0, v83
	v_add_f32_e32 v89, 1.0, v84
	v_add_f32_e32 v90, 1.0, v86
	v_add_f32_e32 v91, 1.0, v85
	v_rcp_f32_e32 v82, v15
	v_rcp_f32_e32 v83, v57
	v_rcp_f32_e32 v84, v75
	v_rcp_f32_e32 v85, v87
	v_rcp_f32_e32 v86, v88
	v_rcp_f32_e32 v87, v89
	v_rcp_f32_e32 v88, v90
	v_rcp_f32_e32 v89, v91
	v_mul_f32_e32 v15, 0x4b800000, v14
	v_cndmask_b32_e32 v14, v14, v15, vcc
	v_rsq_f32_e32 v14, v14
	s_waitcnt vmcnt(10)
	v_pk_mul_f32 v[24:25], v[24:25], v[156:157]
	v_pk_mul_f32 v[26:27], v[26:27], v[158:159]
	s_waitcnt vmcnt(9)
	v_pk_mul_f32 v[10:11], v[10:11], v[160:161]
	v_pk_mul_f32 v[12:13], v[12:13], v[162:163]
	v_pk_mul_f32 v[24:25], v[24:25], v[82:83]
	v_pk_mul_f32 v[26:27], v[26:27], v[84:85]
	v_pk_mul_f32 v[60:61], v[10:11], v[86:87]
	v_pk_mul_f32 v[62:63], v[12:13], v[88:89]
	v_cvt_pk_bf16_f32 v10, v24, v25
	v_cvt_pk_bf16_f32 v11, v26, v27
	v_cvt_pk_bf16_f32 v12, v60, v61
	v_cvt_pk_bf16_f32 v13, v62, v63
	s_nop 0
	v_permlane32_swap_b32_e32 v10, v12
	v_permlane32_swap_b32_e32 v11, v13
	global_store_dwordx4 v[28:29], v[10:13], off offset:1056
	s_nop 0
	v_mul_f32_e32 v15, 0x45800000, v14
	v_cndmask_b32_e32 v62, v14, v15, vcc
	v_pk_mul_f32 v[14:15], v[16:17], v[62:63] op_sel_hi:[1,0]
	v_pk_mul_f32 v[16:17], v[18:19], v[62:63] op_sel_hi:[1,0]
	v_pk_mul_f32 v[18:19], v[20:21], v[62:63] op_sel_hi:[1,0]
	v_pk_mul_f32 v[20:21], v[22:23], v[62:63] op_sel_hi:[1,0]
	v_lshl_add_u64 v[28:29], v[30:31], 0, v[36:37]
	s_waitcnt vmcnt(9)
	v_lshlrev_b32_e32 v22, 16, v164
	v_and_b32_e32 v23, 0xffff0000, v164
	v_lshlrev_b32_e32 v57, 16, v165
	v_and_b32_e32 v63, 0xffff0000, v165
	s_waitcnt vmcnt(8)
	v_lshlrev_b32_e32 v64, 16, v166
	v_and_b32_e32 v65, 0xffff0000, v166
	v_lshlrev_b32_e32 v66, 16, v167
	v_and_b32_e32 v67, 0xffff0000, v167
	v_mul_f32_e32 v22, 0xbfb8aa3b, v22
	v_mul_f32_e32 v23, 0xbfb8aa3b, v23
	v_mul_f32_e32 v57, 0xbfb8aa3b, v57
	v_mul_f32_e32 v63, 0xbfb8aa3b, v63
	v_mul_f32_e32 v64, 0xbfb8aa3b, v64
	v_mul_f32_e32 v65, 0xbfb8aa3b, v65
	v_mul_f32_e32 v66, 0xbfb8aa3b, v66
	v_mul_f32_e32 v67, 0xbfb8aa3b, v67
	v_exp_f32_e32 v22, v22
	v_exp_f32_e32 v23, v23
	v_exp_f32_e32 v57, v57
	v_exp_f32_e32 v63, v63
	v_exp_f32_e32 v64, v64
	v_exp_f32_e32 v65, v65
	v_exp_f32_e32 v66, v66
	v_exp_f32_e32 v67, v67
	v_add_f32_e32 v22, 1.0, v22
	v_add_f32_e32 v23, 1.0, v23
	v_add_f32_e32 v57, 1.0, v57
	v_add_f32_e32 v63, 1.0, v63
	v_add_f32_e32 v75, 1.0, v64
	v_add_f32_e32 v76, 1.0, v65
	v_add_f32_e32 v77, 1.0, v66
	v_add_f32_e32 v78, 1.0, v67
	v_rcp_f32_e32 v22, v22
	v_rcp_f32_e32 v23, v23
	v_rcp_f32_e32 v64, v57
	v_rcp_f32_e32 v65, v63
	v_rcp_f32_e32 v66, v75
	v_rcp_f32_e32 v67, v76
	v_rcp_f32_e32 v76, v77
	v_rcp_f32_e32 v77, v78
	v_pk_mul_f32 v[0:1], v[0:1], v[62:63] op_sel_hi:[1,0]
	v_pk_mul_f32 v[2:3], v[2:3], v[62:63] op_sel_hi:[1,0]
	v_pk_mul_f32 v[4:5], v[4:5], v[62:63] op_sel_hi:[1,0]
	v_pk_mul_f32 v[6:7], v[6:7], v[62:63] op_sel_hi:[1,0]
	s_waitcnt vmcnt(7)
	v_pk_mul_f32 v[10:11], v[14:15], v[168:169]
	v_pk_mul_f32 v[12:13], v[16:17], v[170:171]
	s_waitcnt vmcnt(6)
	v_pk_mul_f32 v[14:15], v[18:19], v[172:173]
	v_pk_mul_f32 v[16:17], v[20:21], v[174:175]
	v_pk_mul_f32 v[10:11], v[10:11], v[22:23]
	v_pk_mul_f32 v[12:13], v[12:13], v[64:65]
	v_pk_mul_f32 v[14:15], v[14:15], v[66:67]
	v_pk_mul_f32 v[16:17], v[16:17], v[76:77]
	v_cvt_pk_bf16_f32 v10, v10, v11
	v_cvt_pk_bf16_f32 v11, v12, v13
	v_cvt_pk_bf16_f32 v12, v14, v15
	v_cvt_pk_bf16_f32 v13, v16, v17
	s_nop 0
	v_permlane32_swap_b32_e32 v10, v12
	v_permlane32_swap_b32_e32 v11, v13
	global_store_dwordx4 v[28:29], v[10:13], off
	s_nop 0
	s_waitcnt vmcnt(6)
	v_lshlrev_b32_e32 v8, 16, v176
	v_and_b32_e32 v9, 0xffff0000, v176
	v_lshlrev_b32_e32 v18, 16, v177
	v_and_b32_e32 v19, 0xffff0000, v177
	s_waitcnt vmcnt(5)
	v_lshlrev_b32_e32 v20, 16, v178
	v_and_b32_e32 v21, 0xffff0000, v178
	v_lshlrev_b32_e32 v22, 16, v179
	v_and_b32_e32 v23, 0xffff0000, v179
	v_mul_f32_e32 v8, 0xbfb8aa3b, v8
	v_mul_f32_e32 v9, 0xbfb8aa3b, v9
	v_mul_f32_e32 v18, 0xbfb8aa3b, v18
	v_mul_f32_e32 v19, 0xbfb8aa3b, v19
	v_mul_f32_e32 v20, 0xbfb8aa3b, v20
	v_mul_f32_e32 v21, 0xbfb8aa3b, v21
	v_mul_f32_e32 v22, 0xbfb8aa3b, v22
	v_mul_f32_e32 v23, 0xbfb8aa3b, v23
	v_exp_f32_e32 v8, v8
	v_exp_f32_e32 v9, v9
	v_exp_f32_e32 v18, v18
	v_exp_f32_e32 v19, v19
	v_exp_f32_e32 v20, v20
	v_exp_f32_e32 v21, v21
	v_exp_f32_e32 v22, v22
	v_exp_f32_e32 v23, v23
	v_add_f32_e32 v8, 1.0, v8
	v_add_f32_e32 v9, 1.0, v9
	v_add_f32_e32 v18, 1.0, v18
	v_add_f32_e32 v19, 1.0, v19
	v_add_f32_e32 v20, 1.0, v20
	v_add_f32_e32 v21, 1.0, v21
	v_add_f32_e32 v22, 1.0, v22
	v_add_f32_e32 v23, 1.0, v23
	v_rcp_f32_e32 v8, v8
	v_rcp_f32_e32 v9, v9
	v_rcp_f32_e32 v18, v18
	v_rcp_f32_e32 v19, v19
	v_rcp_f32_e32 v20, v20
	v_rcp_f32_e32 v21, v21
	v_rcp_f32_e32 v22, v22
	v_rcp_f32_e32 v23, v23
	s_waitcnt vmcnt(4)
	v_pk_mul_f32 v[0:1], v[0:1], v[180:181]
	v_pk_mul_f32 v[2:3], v[2:3], v[182:183]
	s_waitcnt vmcnt(3)
	v_pk_mul_f32 v[4:5], v[4:5], v[184:185]
	v_pk_mul_f32 v[6:7], v[6:7], v[186:187]
	v_pk_mul_f32 v[0:1], v[0:1], v[8:9]
	v_pk_mul_f32 v[2:3], v[2:3], v[18:19]
	v_pk_mul_f32 v[4:5], v[4:5], v[20:21]
	v_pk_mul_f32 v[6:7], v[6:7], v[22:23]
	v_cvt_pk_bf16_f32 v0, v0, v1
	v_cvt_pk_bf16_f32 v1, v2, v3
	v_cvt_pk_bf16_f32 v2, v4, v5
	v_cvt_pk_bf16_f32 v3, v6, v7
	s_nop 0
	v_permlane32_swap_b32_e32 v0, v2
	v_permlane32_swap_b32_e32 v1, v3
	global_store_dwordx4 v[28:29], v[0:3], off offset:32
	s_barrier
	s_cbranch_scc0 .LBB0_1653
